# attention finalize group 1: first pool-weight fragment loads hoisted above the exchange barrier
# baseline (speedup 1.0000x reference)
; __device__ __forceinline__ void attn_unit_pp(int b, int h, int qb, int par, const bf16_t* __restrict__ QBp, const bf16_t* __restrict__ KBp, const bf16_t* __restrict__ VBp, ...
;     ...
;   if (g == 1) {
;     unsigned gate16[64];
; #pragma unroll
;     for (int r = 0; r < 16; ++r)
; #pragma unroll
;       for (int d0 = 0; d0 < 4; ++d0) gate16[r * 4 + d0] = GATE_LD((r & 3) + 8 * (r >> 2), 1024 + d0 * 32);
;     bf16x8 pf[8];
;     { const bf16_t* pr = PLDp + (size_t)(rowbase + q0 + w4 * QBLK + r32) * 512 + (h >> 1) * 128 + hi * 8;
; #pragma unroll
;       for (int ks = 0; ks < 8; ++ks) pf[ks] = ld8(pr + ks * 16); }
; #pragma unroll
;     for (int d0 = 0; d0 < 4; ++d0)
; #pragma unroll
;       for (int r = 0; r < 16; ++r) xs[(d0 * 16 + r) * 64] = o[d0][r];
.LBB0_412:
	v_add_u32_e32 v35, 0x800, v34
	v_add_u32_e32 v36, 0x840, v34
	v_add_u32_e32 v37, 0x880, v34
	v_add_u32_e32 v38, 0x8c0, v34
	v_add_u32_e32 v39, 0x1800, v34
	v_add_u32_e32 v40, 0x1840, v34
	v_add_u32_e32 v41, 0x1880, v34
	v_add_u32_e32 v42, 0x18c0, v34
	global_load_ushort v149, v35, s[20:21]
	global_load_ushort v133, v36, s[20:21]
	global_load_ushort v122, v37, s[20:21]
	global_load_ushort v102, v38, s[20:21]
	global_load_ushort v150, v39, s[20:21]
	global_load_ushort v134, v40, s[20:21]
	global_load_ushort v120, v41, s[20:21]
	global_load_ushort v101, v42, s[20:21]
	v_add_u32_e32 v35, 0x2800, v34
	v_add_u32_e32 v36, 0x2840, v34
	v_add_u32_e32 v37, 0x2880, v34
	v_add_u32_e32 v38, 0x28c0, v34
	v_add_u32_e32 v39, 0x3800, v34
	v_add_u32_e32 v40, 0x3840, v34
	v_add_u32_e32 v41, 0x3880, v34
	v_add_u32_e32 v42, 0x38c0, v34
	global_load_ushort v151, v35, s[20:21]
	global_load_ushort v136, v36, s[20:21]
	global_load_ushort v126, v37, s[20:21]
	global_load_ushort v104, v38, s[20:21]
	global_load_ushort v152, v39, s[20:21]
	global_load_ushort v135, v40, s[20:21]
	global_load_ushort v125, v41, s[20:21]
	global_load_ushort v103, v42, s[20:21]
	v_add_u32_e32 v35, 0x8800, v34
	v_add_u32_e32 v36, 0x8840, v34
	v_add_u32_e32 v37, 0x8880, v34
	v_add_u32_e32 v38, 0x88c0, v34
	v_add_u32_e32 v39, 0x9800, v34
	v_add_u32_e32 v40, 0x9840, v34
	v_add_u32_e32 v41, 0x9880, v34
	v_add_u32_e32 v42, 0x98c0, v34
	global_load_ushort v153, v35, s[20:21]
	global_load_ushort v138, v36, s[20:21]
	global_load_ushort v128, v37, s[20:21]
	global_load_ushort v106, v38, s[20:21]
	global_load_ushort v154, v39, s[20:21]
	global_load_ushort v137, v40, s[20:21]
	global_load_ushort v127, v41, s[20:21]
	global_load_ushort v105, v42, s[20:21]
	v_add_u32_e32 v35, 0xa800, v34
	v_add_u32_e32 v36, 0xa840, v34
	v_add_u32_e32 v37, 0xa880, v34
	v_add_u32_e32 v38, 0xa8c0, v34
	v_add_u32_e32 v39, 0xb800, v34
	v_add_u32_e32 v40, 0xb840, v34
	v_add_u32_e32 v41, 0xb880, v34
	v_or_b32_e32 v2, v2, v179
	v_add_u32_e32 v42, 0xb8c0, v34
	global_load_ushort v155, v35, s[20:21]
	global_load_ushort v140, v36, s[20:21]
	global_load_ushort v130, v37, s[20:21]
	global_load_ushort v108, v38, s[20:21]
	global_load_ushort v156, v39, s[20:21]
	global_load_ushort v139, v40, s[20:21]
	global_load_ushort v129, v41, s[20:21]
	global_load_ushort v107, v42, s[20:21]
	v_add_u32_e32 v35, 0x10800, v34
	v_add_u32_e32 v36, 0x10840, v34
	v_add_u32_e32 v37, 0x10880, v34
	v_add_u32_e32 v38, 0x108c0, v34
	v_add_u32_e32 v39, 0x11800, v34
	v_add_u32_e32 v40, 0x11840, v34
	v_add_u32_e32 v41, 0x11880, v34
	v_lshlrev_b64 v[2:3], 10, v[2:3]
	v_add_u32_e32 v42, 0x118c0, v34
	global_load_ushort v157, v35, s[20:21]
	global_load_ushort v141, v36, s[20:21]
	global_load_ushort v132, v37, s[20:21]
	global_load_ushort v110, v38, s[20:21]
	global_load_ushort v158, v39, s[20:21]
	global_load_ushort v142, v40, s[20:21]
	global_load_ushort v131, v41, s[20:21]
	global_load_ushort v109, v42, s[20:21]
	v_add_u32_e32 v35, 0x12800, v34
	v_add_u32_e32 v36, 0x12840, v34
	v_add_u32_e32 v37, 0x12880, v34
	v_add_u32_e32 v38, 0x128c0, v34
	v_add_u32_e32 v39, 0x13800, v34
	v_add_u32_e32 v40, 0x13840, v34
	v_add_u32_e32 v41, 0x13880, v34
	v_lshl_add_u64 v[2:3], s[56:57], 0, v[2:3]
	s_and_b32 s6, s10, 0x300
	v_add_u32_e32 v42, 0x138c0, v34
	global_load_ushort v159, v35, s[20:21]
	global_load_ushort v147, v36, s[20:21]
	global_load_ushort v118, v37, s[20:21]
	global_load_ushort v112, v38, s[20:21]
	global_load_ushort v160, v39, s[20:21]
	global_load_ushort v143, v40, s[20:21]
	global_load_ushort v117, v41, s[20:21]
	global_load_ushort v111, v42, s[20:21]
	v_add_u32_e32 v35, 0x18800, v34
	v_add_u32_e32 v36, 0x18840, v34
	v_add_u32_e32 v37, 0x18880, v34
	v_add_u32_e32 v38, 0x188c0, v34
	v_add_u32_e32 v39, 0x19800, v34
	v_add_u32_e32 v40, 0x19840, v34
	v_add_u32_e32 v41, 0x19880, v34
	v_lshl_add_u64 v[2:3], v[2:3], 0, s[6:7]
	v_mov_b32_e32 v169, v1
	s_and_b32 s0, s10, 0x80
	v_add_u32_e32 v42, 0x198c0, v34
	global_load_ushort v161, v35, s[20:21]
	global_load_ushort v144, v36, s[20:21]
	global_load_ushort v121, v37, s[20:21]
	global_load_ushort v114, v38, s[20:21]
	global_load_ushort v162, v39, s[20:21]
	global_load_ushort v145, v40, s[20:21]
	global_load_ushort v119, v41, s[20:21]
	global_load_ushort v113, v42, s[20:21]
	v_add_u32_e32 v35, 0x1a800, v34
	v_add_u32_e32 v36, 0x1a840, v34
	v_add_u32_e32 v37, 0x1a880, v34
	v_add_u32_e32 v38, 0x1a8c0, v34
	v_add_u32_e32 v39, 0x1b800, v34
	v_add_u32_e32 v40, 0x1b840, v34
	v_add_u32_e32 v41, 0x1b880, v34
	v_add_u32_e32 v34, 0x1b8c0, v34
	v_lshl_add_u64 v[2:3], v[2:3], 0, v[168:169]
	s_or_b32 s0, s6, s0
	global_load_ushort v163, v35, s[20:21]
	global_load_ushort v148, v36, s[20:21]
	global_load_ushort v123, v37, s[20:21]
	global_load_ushort v116, v38, s[20:21]
	global_load_ushort v164, v39, s[20:21]
	global_load_ushort v146, v40, s[20:21]
	global_load_ushort v124, v41, s[20:21]
	global_load_ushort v115, v34, s[20:21]
	global_load_dwordx4 v[62:65], v[2:3], off
	global_load_dwordx4 v[58:61], v[2:3], off offset:32
	global_load_dwordx4 v[54:57], v[2:3], off offset:64
	global_load_dwordx4 v[50:53], v[2:3], off offset:96
	global_load_dwordx4 v[46:49], v[2:3], off offset:128
	global_load_dwordx4 v[42:45], v[2:3], off offset:160
	global_load_dwordx4 v[38:41], v[2:3], off offset:192
	global_load_dwordx4 v[34:37], v[2:3], off offset:224
	ds_write2st64_b32 v78, v9, v13 offset1:1
	ds_write2st64_b32 v78, v17, v32 offset0:2 offset1:3
	ds_write2st64_b32 v78, v67, v80 offset0:4 offset1:5
	ds_write2st64_b32 v78, v82, v22 offset0:6 offset1:7
	ds_write2st64_b32 v78, v86, v88 offset0:8 offset1:9
	ds_write2st64_b32 v78, v90, v91 offset0:10 offset1:11
; __device__ __forceinline__ float sigm_(float x) { return __builtin_amdgcn_rcpf(1.0f + __builtin_amdgcn_exp2f(-1.4426950408889634f * x)); }
; __device__ __forceinline__ void attn_unit_pp(int b, int h, int qb, int par, const bf16_t* __restrict__ QBp, const bf16_t* __restrict__ KBp, const bf16_t* __restrict__ VBp, ...
;     ...
;     __syncthreads();
;     const bf16_t* wpb = WPLp + (size_t)((h >> 1) * 256 + (h & 1) * 128 + r32) * 128 + hi * 8;
; #pragma unroll
;     for (int dp = 0; dp < 2; ++dp) {
;       bf16x8 wp[2][8];
; #pragma unroll
;       for (int e = 0; e < 2; ++e)
; #pragma unroll
;         for (int ks = 0; ks < 8; ++ks) wp[e][ks] = ld8(wpb + (dp * 2 + e) * 32 * 128 + ks * 16);
; #pragma unroll
;       for (int e = 0; e < 2; ++e) { const int d0 = dp * 2 + e; f32x16 acc = f32x16{};
; #pragma unroll
;         for (int ks = 0; ks < 8; ++ks) acc = __builtin_amdgcn_mfma_f32_32x32x16_bf16(pf[ks], wp[e][ks], acc, 0, 0, 0);
; #pragma unroll
;         for (int r = 0; r < 16; ++r) pgs[(d0 * 16 + r) * 64] = sigm_(__uint_as_float(gate16[r * 4 + d0] << 16)) * acc[r]; }
	ds_write2st64_b32 v78, v93, v96 offset0:12 offset1:13
	ds_write2st64_b32 v78, v98, v100 offset0:14 offset1:15
	ds_write2st64_b32 v78, v6, v10 offset0:16 offset1:17
	ds_write2st64_b32 v78, v14, v18 offset0:18 offset1:19
	ds_write2st64_b32 v78, v33, v69 offset0:20 offset1:21
	ds_write2st64_b32 v78, v70, v83 offset0:22 offset1:23
	ds_write2st64_b32 v78, v84, v85 offset0:24 offset1:25
	ds_write2st64_b32 v78, v87, v89 offset0:26 offset1:27
	ds_write2st64_b32 v78, v92, v94 offset0:28 offset1:29
	ds_write2st64_b32 v78, v97, v99 offset0:30 offset1:31
	ds_write2st64_b32 v78, v4, v7 offset0:32 offset1:33
	ds_write2st64_b32 v78, v11, v15 offset0:34 offset1:35
	ds_write2st64_b32 v78, v19, v66 offset0:36 offset1:37
	ds_write2st64_b32 v78, v81, v71 offset0:38 offset1:39
	ds_write2st64_b32 v78, v72, v73 offset0:40 offset1:41
	ds_write2st64_b32 v78, v74, v75 offset0:42 offset1:43
	ds_write2st64_b32 v78, v76, v77 offset0:44 offset1:45
	ds_write2st64_b32 v78, v95, v79 offset0:46 offset1:47
	ds_write2st64_b32 v78, v0, v5 offset0:48 offset1:49
	ds_write2st64_b32 v78, v8, v12 offset0:50 offset1:51
	ds_write2st64_b32 v78, v16, v20 offset0:52 offset1:53
	ds_write2st64_b32 v78, v21, v23 offset0:54 offset1:55
	ds_write2st64_b32 v78, v24, v25 offset0:56 offset1:57
	ds_write2st64_b32 v78, v26, v27 offset0:58 offset1:59
	ds_write2st64_b32 v78, v28, v29 offset0:60 offset1:61
	ds_write2st64_b32 v78, v30, v31 offset0:62 offset1:63
	v_or_b32_e32 v0, s0, v179
	v_readlane_b32 s0, v238, 14
	v_lshlrev_b32_e32 v0, 8, v0
	v_readlane_b32 s1, v238, 15
	s_nop 1
	v_lshl_add_u64 v[2:3], s[0:1], 0, v[0:1]
	v_lshl_add_u64 v[66:67], v[2:3], 0, v[168:169]
	global_load_dwordx4 v[2:5], v[66:67], off
	global_load_dwordx4 v[6:9], v[66:67], off offset:32
	global_load_dwordx4 v[26:29], v[66:67], off offset:64
	global_load_dwordx4 v[30:33], v[66:67], off offset:96
	s_waitcnt lgkmcnt(0)
	s_barrier
	s_waitcnt vmcnt(3)
	v_mfma_f32_32x32x16_bf16 v[10:25], v[62:65], v[2:5], 0
	global_load_dwordx4 v[2:5], v[66:67], off offset:128
	v_add_co_u32_e32 v90, vcc, s61, v66
	v_lshlrev_b32_e32 v0, 16, v149
	s_nop 0
	v_addc_co_u32_e32 v91, vcc, 0, v67, vcc
	v_mul_f32_e32 v0, 0xbfb8aa3b, v0
	s_waitcnt vmcnt(3)
	v_mfma_f32_32x32x16_bf16 v[10:25], v[58:61], v[6:9], v[10:25]
	global_load_dwordx4 v[6:9], v[66:67], off offset:160
	v_exp_f32_e32 v0, v0
	s_nop 0
	v_add_f32_e32 v0, 1.0, v0
	v_rcp_f32_e32 v0, v0
	s_waitcnt vmcnt(3)
	v_mfma_f32_32x32x16_bf16 v[10:25], v[54:57], v[26:29], v[10:25]
	global_load_dwordx4 v[26:29], v[66:67], off offset:192
	s_waitcnt vmcnt(3)
	v_mfma_f32_32x32x16_bf16 v[10:25], v[50:53], v[30:33], v[10:25]
	global_load_dwordx4 v[30:33], v[66:67], off offset:224
	s_waitcnt vmcnt(3)
	v_mfma_f32_32x32x16_bf16 v[10:25], v[46:49], v[2:5], v[10:25]
	global_load_dwordx4 v[2:5], v[90:91], off
	global_load_dwordx4 v[70:73], v[90:91], off offset:32
	global_load_dwordx4 v[74:77], v[90:91], off offset:64
	global_load_dwordx4 v[78:81], v[90:91], off offset:96
	global_load_dwordx4 v[82:85], v[90:91], off offset:128
	global_load_dwordx4 v[86:89], v[90:91], off offset:160
	s_waitcnt vmcnt(8)
	v_mfma_f32_32x32x16_bf16 v[10:25], v[42:45], v[6:9], v[10:25]
	v_lshlrev_b32_e32 v6, 16, v150
	v_mul_f32_e32 v6, 0xbfb8aa3b, v6
	v_exp_f32_e32 v6, v6
	v_lshlrev_b32_e32 v7, 16, v151
	v_mul_f32_e32 v7, 0xbfb8aa3b, v7
	v_exp_f32_e32 v7, v7
	v_add_f32_e32 v6, 1.0, v6
	s_waitcnt vmcnt(7)
	v_mfma_f32_32x32x16_bf16 v[10:25], v[38:41], v[26:29], v[10:25]
	global_load_dwordx4 v[26:29], v[90:91], off offset:192
	s_nop 0
	global_load_dwordx4 v[90:93], v[90:91], off offset:224
	v_rcp_f32_e32 v6, v6
	v_lshlrev_b32_e32 v8, 16, v154
	v_mul_f32_e32 v8, 0xbfb8aa3b, v8
	v_exp_f32_e32 v8, v8
	s_waitcnt vmcnt(8)
	v_mfma_f32_32x32x16_bf16 v[10:25], v[34:37], v[30:33], v[10:25]
	v_lshlrev_b32_e32 v32, 16, v158
	v_mul_f32_e32 v32, 0xbfb8aa3b, v32
	v_exp_f32_e32 v32, v32
	s_nop 8
	v_mul_f32_e32 v0, v0, v10
	v_mul_f32_e32 v6, v6, v11
	ds_write2st64_b32 v68, v0, v6 offset1:1
	v_lshlrev_b32_e32 v6, 16, v152
	v_add_f32_e32 v0, 1.0, v7
	v_mul_f32_e32 v6, 0xbfb8aa3b, v6
	v_lshlrev_b32_e32 v7, 16, v153
	v_exp_f32_e32 v6, v6
	v_mul_f32_e32 v7, 0xbfb8aa3b, v7
	v_exp_f32_e32 v7, v7
	v_rcp_f32_e32 v0, v0
	v_add_f32_e32 v6, 1.0, v6
	v_rcp_f32_e32 v6, v6
	v_add_f32_e32 v7, 1.0, v7
	v_rcp_f32_e32 v7, v7
	v_mul_f32_e32 v0, v0, v12
	v_mul_f32_e32 v6, v6, v13
	ds_write2st64_b32 v68, v0, v6 offset0:2 offset1:3
	v_mul_f32_e32 v0, v7, v14
	v_add_f32_e32 v6, 1.0, v8
	v_lshlrev_b32_e32 v7, 16, v155
	v_lshlrev_b32_e32 v8, 16, v156
	v_mul_f32_e32 v7, 0xbfb8aa3b, v7
	v_mul_f32_e32 v8, 0xbfb8aa3b, v8
	v_exp_f32_e32 v7, v7
	v_exp_f32_e32 v8, v8
	v_rcp_f32_e32 v6, v6
	v_add_f32_e32 v7, 1.0, v7
	v_add_f32_e32 v8, 1.0, v8
	v_rcp_f32_e32 v7, v7
	v_rcp_f32_e32 v8, v8
	v_mul_f32_e32 v6, v6, v15
	ds_write2st64_b32 v68, v0, v6 offset0:4 offset1:5
	v_lshlrev_b32_e32 v6, 16, v157
	v_mul_f32_e32 v6, 0xbfb8aa3b, v6
	v_mul_f32_e32 v0, v7, v16
	v_mul_f32_e32 v30, v8, v17
	v_exp_f32_e32 v31, v6
	s_waitcnt vmcnt(7)
	v_mfma_f32_32x32x16_bf16 v[2:17], v[62:65], v[2:5], 0
	ds_write2st64_b32 v68, v0, v30 offset0:6 offset1:7
	v_add_f32_e32 v0, 1.0, v31
	v_add_f32_e32 v30, 1.0, v32
	v_rcp_f32_e32 v0, v0
	v_rcp_f32_e32 v30, v30
	v_lshlrev_b32_e32 v31, 16, v159
	v_mul_f32_e32 v31, 0xbfb8aa3b, v31
	s_waitcnt vmcnt(6)
	v_mfma_f32_32x32x16_bf16 v[2:17], v[58:61], v[70:73], v[2:17]
	v_exp_f32_e32 v31, v31
	v_mul_f32_e32 v0, v0, v18
	v_mul_f32_e32 v18, v30, v19
	ds_write2st64_b32 v68, v0, v18 offset0:8 offset1:9
	v_lshlrev_b32_e32 v18, 16, v160
	v_add_f32_e32 v0, 1.0, v31
	v_mul_f32_e32 v18, 0xbfb8aa3b, v18
	s_waitcnt vmcnt(5)
; __device__ __forceinline__ float sigm_(float x) { return __builtin_amdgcn_rcpf(1.0f + __builtin_amdgcn_exp2f(-1.4426950408889634f * x)); }
; __device__ __forceinline__ void attn_unit_pp(int b, int h, int qb, int par, const bf16_t* __restrict__ QBp, const bf16_t* __restrict__ KBp, const bf16_t* __restrict__ VBp, ...
;     ...
;     for (int dp = 0; dp < 2; ++dp) {
;       bf16x8 wp[2][8];
; #pragma unroll
;       for (int e = 0; e < 2; ++e)
; #pragma unroll
;         for (int ks = 0; ks < 8; ++ks) wp[e][ks] = ld8(wpb + (dp * 2 + e) * 32 * 128 + ks * 16);
; #pragma unroll
;       for (int e = 0; e < 2; ++e) { const int d0 = dp * 2 + e; f32x16 acc = f32x16{};
; #pragma unroll
;         for (int ks = 0; ks < 8; ++ks) acc = __builtin_amdgcn_mfma_f32_32x32x16_bf16(pf[ks], wp[e][ks], acc, 0, 0, 0);
; #pragma unroll
;         for (int r = 0; r < 16; ++r) pgs[(d0 * 16 + r) * 64] = sigm_(__uint_as_float(gate16[r * 4 + d0] << 16)) * acc[r]; }
;     }
;     __syncthreads();
	v_mfma_f32_32x32x16_bf16 v[2:17], v[54:57], v[74:77], v[2:17]
	v_lshlrev_b32_e32 v19, 16, v161
	v_rcp_f32_e32 v0, v0
	v_exp_f32_e32 v18, v18
	v_mul_f32_e32 v19, 0xbfb8aa3b, v19
	v_exp_f32_e32 v19, v19
	v_mul_f32_e32 v0, v0, v20
	v_add_f32_e32 v18, 1.0, v18
	s_waitcnt vmcnt(4)
	v_mfma_f32_32x32x16_bf16 v[2:17], v[50:53], v[78:81], v[2:17]
	v_lshlrev_b32_e32 v20, 16, v162
	v_rcp_f32_e32 v18, v18
	v_add_f32_e32 v19, 1.0, v19
	v_mul_f32_e32 v20, 0xbfb8aa3b, v20
	v_rcp_f32_e32 v19, v19
	v_exp_f32_e32 v20, v20
	v_mul_f32_e32 v18, v18, v21
	ds_write2st64_b32 v68, v0, v18 offset0:10 offset1:11
	v_mul_f32_e32 v0, v19, v22
	v_add_f32_e32 v18, 1.0, v20
	v_lshlrev_b32_e32 v19, 16, v163
	v_lshlrev_b32_e32 v20, 16, v164
	s_waitcnt vmcnt(3)
	v_mfma_f32_32x32x16_bf16 v[2:17], v[46:49], v[82:85], v[2:17]
	v_mul_f32_e32 v19, 0xbfb8aa3b, v19
	v_mul_f32_e32 v20, 0xbfb8aa3b, v20
	v_exp_f32_e32 v19, v19
	v_exp_f32_e32 v20, v20
	v_rcp_f32_e32 v18, v18
	v_add_co_u32_e32 v22, vcc, s58, v66
	v_add_f32_e32 v19, 1.0, v19
	v_add_f32_e32 v20, 1.0, v20
	v_rcp_f32_e32 v19, v19
	v_rcp_f32_e32 v20, v20
	s_waitcnt vmcnt(2)
	v_mfma_f32_32x32x16_bf16 v[2:17], v[42:45], v[86:89], v[2:17]
	v_mul_f32_e32 v18, v18, v23
	ds_write2st64_b32 v68, v0, v18 offset0:12 offset1:13
	v_mul_f32_e32 v0, v19, v24
	v_mul_f32_e32 v18, v20, v25
	v_addc_co_u32_e32 v23, vcc, 0, v67, vcc
	ds_write2st64_b32 v68, v0, v18 offset0:14 offset1:15
	global_load_dwordx4 v[18:21], v[22:23], off
	global_load_dwordx4 v[70:73], v[22:23], off offset:32
	s_waitcnt vmcnt(3)
	v_mfma_f32_32x32x16_bf16 v[2:17], v[38:41], v[26:29], v[2:17]
	v_lshlrev_b32_e32 v0, 16, v133
	v_lshlrev_b32_e32 v24, 16, v134
	v_mul_f32_e32 v0, 0xbfb8aa3b, v0
	v_mul_f32_e32 v24, 0xbfb8aa3b, v24
	v_exp_f32_e32 v0, v0
	v_exp_f32_e32 v24, v24
	global_load_dwordx4 v[74:77], v[22:23], off offset:64
	global_load_dwordx4 v[78:81], v[22:23], off offset:96
	s_waitcnt vmcnt(4)
	v_mfma_f32_32x32x16_bf16 v[2:17], v[34:37], v[90:93], v[2:17]
	v_add_f32_e32 v0, 1.0, v0
	v_add_f32_e32 v24, 1.0, v24
	v_rcp_f32_e32 v0, v0
	v_rcp_f32_e32 v24, v24
	v_lshlrev_b32_e32 v25, 16, v136
	v_mul_f32_e32 v25, 0xbfb8aa3b, v25
	v_exp_f32_e32 v25, v25
	s_nop 4
	v_mul_f32_e32 v0, v0, v2
	v_mul_f32_e32 v2, v24, v3
	v_lshlrev_b32_e32 v24, 16, v135
	v_mul_f32_e32 v24, 0xbfb8aa3b, v24
	v_exp_f32_e32 v24, v24
	v_add_f32_e32 v3, 1.0, v25
	v_rcp_f32_e32 v3, v3
	ds_write2st64_b32 v68, v0, v2 offset0:16 offset1:17
	v_add_f32_e32 v2, 1.0, v24
	v_rcp_f32_e32 v2, v2
	v_mul_f32_e32 v0, v3, v4
	v_lshlrev_b32_e32 v3, 16, v138
	v_mul_f32_e32 v3, 0xbfb8aa3b, v3
	v_exp_f32_e32 v24, v3
	v_mul_f32_e32 v25, v2, v5
	global_load_dwordx4 v[2:5], v[22:23], off offset:128
	global_load_dwordx4 v[82:85], v[22:23], off offset:160
	global_load_dwordx4 v[86:89], v[22:23], off offset:192
	global_load_dwordx4 v[90:93], v[22:23], off offset:224
	ds_write2st64_b32 v68, v0, v25 offset0:18 offset1:19
	v_add_f32_e32 v0, 1.0, v24
	v_lshlrev_b32_e32 v24, 16, v137
	v_lshlrev_b32_e32 v25, 16, v140
	v_mul_f32_e32 v24, 0xbfb8aa3b, v24
	v_mul_f32_e32 v25, 0xbfb8aa3b, v25
	v_rcp_f32_e32 v0, v0
	v_exp_f32_e32 v24, v24
	v_exp_f32_e32 v25, v25
	v_mul_f32_e32 v0, v0, v6
	v_add_f32_e32 v6, 1.0, v24
	v_add_f32_e32 v24, 1.0, v25
	v_lshlrev_b32_e32 v25, 16, v139
	v_rcp_f32_e32 v6, v6
	v_mul_f32_e32 v25, 0xbfb8aa3b, v25
	v_rcp_f32_e32 v24, v24
	v_exp_f32_e32 v25, v25
	v_mul_f32_e32 v6, v6, v7
	ds_write2st64_b32 v68, v0, v6 offset0:20 offset1:21
	v_mul_f32_e32 v0, v24, v8
	v_add_f32_e32 v6, 1.0, v25
	s_waitcnt vmcnt(7)
	v_mfma_f32_32x32x16_bf16 v[18:33], v[62:65], v[18:21], 0
	v_lshlrev_b32_e32 v8, 16, v142
	v_lshlrev_b32_e32 v7, 16, v141
	v_mul_f32_e32 v8, 0xbfb8aa3b, v8
	v_rcp_f32_e32 v6, v6
	v_mul_f32_e32 v7, 0xbfb8aa3b, v7
	v_exp_f32_e32 v8, v8
	v_exp_f32_e32 v7, v7
	s_waitcnt vmcnt(6)
	v_mfma_f32_32x32x16_bf16 v[18:33], v[58:61], v[70:73], v[18:33]
	v_mul_f32_e32 v6, v6, v9
	v_add_f32_e32 v8, 1.0, v8
	v_lshlrev_b32_e32 v9, 16, v147
	v_add_f32_e32 v7, 1.0, v7
	v_rcp_f32_e32 v8, v8
	v_mul_f32_e32 v9, 0xbfb8aa3b, v9
	v_rcp_f32_e32 v7, v7
	v_exp_f32_e32 v9, v9
	ds_write2st64_b32 v68, v0, v6 offset0:22 offset1:23
	v_mul_f32_e32 v6, v8, v11
	v_lshlrev_b32_e32 v8, 16, v143
	v_mul_f32_e32 v0, v7, v10
	v_add_f32_e32 v7, 1.0, v9
	v_mul_f32_e32 v8, 0xbfb8aa3b, v8
	v_rcp_f32_e32 v7, v7
	v_exp_f32_e32 v8, v8
	s_waitcnt vmcnt(5)
	v_mfma_f32_32x32x16_bf16 v[18:33], v[54:57], v[74:77], v[18:33]
	ds_write2st64_b32 v68, v0, v6 offset0:24 offset1:25
	v_mul_f32_e32 v0, v7, v12
	v_add_f32_e32 v6, 1.0, v8
	v_lshlrev_b32_e32 v7, 16, v144
	v_mul_f32_e32 v7, 0xbfb8aa3b, v7
	v_rcp_f32_e32 v6, v6
	v_exp_f32_e32 v7, v7
	s_waitcnt vmcnt(4)
	v_mfma_f32_32x32x16_bf16 v[18:33], v[50:53], v[78:81], v[18:33]
	v_lshlrev_b32_e32 v8, 16, v145
	v_mul_f32_e32 v6, v6, v13
	v_add_f32_e32 v7, 1.0, v7
	ds_write2st64_b32 v68, v0, v6 offset0:26 offset1:27
	v_lshlrev_b32_e32 v6, 16, v148
	v_rcp_f32_e32 v7, v7
	v_mul_f32_e32 v6, 0xbfb8aa3b, v6
	v_exp_f32_e32 v9, v6
	v_lshlrev_b32_e32 v6, 16, v146
	v_mul_f32_e32 v6, 0xbfb8aa3b, v6
	v_exp_f32_e32 v10, v6
	v_add_co_u32_e32 v6, vcc, s67, v66
	v_mul_f32_e32 v0, v7, v14
	s_nop 0
	v_addc_co_u32_e32 v7, vcc, 0, v67, vcc
	s_waitcnt vmcnt(3)
	v_mfma_f32_32x32x16_bf16 v[18:33], v[46:49], v[2:5], v[18:33]
	global_load_dwordx4 v[2:5], v[6:7], off
	global_load_dwordx4 v[70:73], v[6:7], off offset:32
	v_mul_f32_e32 v8, 0xbfb8aa3b, v8
	v_exp_f32_e32 v8, v8
	v_add_f32_e32 v9, 1.0, v9
	v_rcp_f32_e32 v9, v9
	v_add_f32_e32 v8, 1.0, v8
	v_rcp_f32_e32 v8, v8
	s_waitcnt vmcnt(4)
	v_mfma_f32_32x32x16_bf16 v[18:33], v[42:45], v[82:85], v[18:33]
	v_mul_f32_e32 v8, v8, v15
	ds_write2st64_b32 v68, v0, v8 offset0:28 offset1:29
	v_add_f32_e32 v0, 1.0, v10
	v_rcp_f32_e32 v0, v0
	v_mul_f32_e32 v8, v9, v16
	s_waitcnt vmcnt(3)
; __device__ __forceinline__ float sigm_(float x) { return __builtin_amdgcn_rcpf(1.0f + __builtin_amdgcn_exp2f(-1.4426950408889634f * x)); }
; __device__ __forceinline__ void attn_unit_pp(int b, int h, int qb, int par, const bf16_t* __restrict__ QBp, const bf16_t* __restrict__ KBp, const bf16_t* __restrict__ VBp, ...
;     ...
;     for (int dp = 0; dp < 2; ++dp) {
;       bf16x8 wp[2][8];
; #pragma unroll
;       for (int e = 0; e < 2; ++e)
; #pragma unroll
;         for (int ks = 0; ks < 8; ++ks) wp[e][ks] = ld8(wpb + (dp * 2 + e) * 32 * 128 + ks * 16);
; #pragma unroll
;       for (int e = 0; e < 2; ++e) { const int d0 = dp * 2 + e; f32x16 acc = f32x16{};
; #pragma unroll
;         for (int ks = 0; ks < 8; ++ks) acc = __builtin_amdgcn_mfma_f32_32x32x16_bf16(pf[ks], wp[e][ks], acc, 0, 0, 0);
; #pragma unroll
;         for (int r = 0; r < 16; ++r) pgs[(d0 * 16 + r) * 64] = sigm_(__uint_as_float(gate16[r * 4 + d0] << 16)) * acc[r]; }
;     }
;     __syncthreads();
	v_mfma_f32_32x32x16_bf16 v[18:33], v[38:41], v[86:89], v[18:33]
	v_lshlrev_b32_e32 v9, 16, v132
	v_mul_f32_e32 v0, v0, v17
	ds_write2st64_b32 v68, v8, v0 offset0:30 offset1:31
	global_load_dwordx4 v[74:77], v[6:7], off offset:64
	global_load_dwordx4 v[78:81], v[6:7], off offset:96
	global_load_dwordx4 v[82:85], v[6:7], off offset:128
	global_load_dwordx4 v[94:97], v[6:7], off offset:160
	global_load_dwordx4 v[86:89], v[6:7], off offset:192
	global_load_dwordx4 v[134:137], v[6:7], off offset:224
	v_lshlrev_b32_e32 v0, 16, v122
	v_lshlrev_b32_e32 v6, 16, v120
	v_mul_f32_e32 v0, 0xbfb8aa3b, v0
	v_mul_f32_e32 v6, 0xbfb8aa3b, v6
	v_exp_f32_e32 v0, v0
	v_exp_f32_e32 v6, v6
	s_waitcnt vmcnt(8)
	v_mfma_f32_32x32x16_bf16 v[18:33], v[34:37], v[90:93], v[18:33]
	v_lshlrev_b32_e32 v7, 16, v126
	v_add_f32_e32 v0, 1.0, v0
	v_add_f32_e32 v6, 1.0, v6
	v_rcp_f32_e32 v0, v0
	v_rcp_f32_e32 v6, v6
	v_mul_f32_e32 v7, 0xbfb8aa3b, v7
	v_exp_f32_e32 v7, v7
	s_nop 4
	v_mul_f32_e32 v0, v0, v18
	v_mul_f32_e32 v6, v6, v19
	ds_write2st64_b32 v68, v0, v6 offset0:32 offset1:33
	v_lshlrev_b32_e32 v6, 16, v125
	v_add_f32_e32 v0, 1.0, v7
	v_mul_f32_e32 v6, 0xbfb8aa3b, v6
	v_lshlrev_b32_e32 v7, 16, v128
	v_exp_f32_e32 v6, v6
	v_mul_f32_e32 v7, 0xbfb8aa3b, v7
	v_exp_f32_e32 v7, v7
	v_rcp_f32_e32 v0, v0
	v_add_f32_e32 v6, 1.0, v6
	v_rcp_f32_e32 v6, v6
	v_add_f32_e32 v7, 1.0, v7
	v_rcp_f32_e32 v7, v7
	v_lshlrev_b32_e32 v8, 16, v127
	v_mul_f32_e32 v8, 0xbfb8aa3b, v8
	v_mul_f32_e32 v0, v0, v20
	v_exp_f32_e32 v8, v8
	v_mul_f32_e32 v6, v6, v21
	ds_write2st64_b32 v68, v0, v6 offset0:34 offset1:35
	v_mul_f32_e32 v0, v7, v22
	v_lshlrev_b32_e32 v7, 16, v130
	v_mul_f32_e32 v7, 0xbfb8aa3b, v7
	v_exp_f32_e32 v7, v7
	v_add_f32_e32 v6, 1.0, v8
	v_lshlrev_b32_e32 v8, 16, v129
	v_mul_f32_e32 v8, 0xbfb8aa3b, v8
	v_exp_f32_e32 v8, v8
	v_rcp_f32_e32 v6, v6
	v_add_f32_e32 v7, 1.0, v7
	v_mul_f32_e32 v9, 0xbfb8aa3b, v9
	v_rcp_f32_e32 v7, v7
	v_exp_f32_e32 v9, v9
	v_add_f32_e32 v8, 1.0, v8
	v_mul_f32_e32 v6, v6, v23
	v_rcp_f32_e32 v8, v8
	ds_write2st64_b32 v68, v0, v6 offset0:36 offset1:37
	v_mul_f32_e32 v0, v7, v24
	v_add_f32_e32 v7, 1.0, v9
	v_rcp_f32_e32 v7, v7
	v_mul_f32_e32 v6, v8, v25
	v_lshlrev_b32_e32 v8, 16, v131
	v_mul_f32_e32 v8, 0xbfb8aa3b, v8
	v_exp_f32_e32 v18, v8
	ds_write2st64_b32 v68, v0, v6 offset0:38 offset1:39
	v_mul_f32_e32 v0, v7, v26
	s_waitcnt vmcnt(7)
	v_mfma_f32_32x32x16_bf16 v[2:17], v[62:65], v[2:5], 0
	v_add_f32_e32 v18, 1.0, v18
	v_rcp_f32_e32 v18, v18
	v_lshlrev_b32_e32 v19, 16, v118
	v_mul_f32_e32 v19, 0xbfb8aa3b, v19
	v_exp_f32_e32 v19, v19
	v_mul_f32_e32 v18, v18, v27
	ds_write2st64_b32 v68, v0, v18 offset0:40 offset1:41
	s_waitcnt vmcnt(6)
	v_mfma_f32_32x32x16_bf16 v[2:17], v[58:61], v[70:73], v[2:17]
	v_lshlrev_b32_e32 v18, 16, v117
	v_add_f32_e32 v0, 1.0, v19
	v_mul_f32_e32 v18, 0xbfb8aa3b, v18
	v_lshlrev_b32_e32 v19, 16, v121
	v_exp_f32_e32 v18, v18
	v_mul_f32_e32 v19, 0xbfb8aa3b, v19
	v_exp_f32_e32 v19, v19
	s_waitcnt vmcnt(5)
	v_mfma_f32_32x32x16_bf16 v[2:17], v[54:57], v[74:77], v[2:17]
	v_add_f32_e32 v18, 1.0, v18
	v_lshlrev_b32_e32 v20, 16, v119
	v_rcp_f32_e32 v0, v0
	v_rcp_f32_e32 v18, v18
	v_add_f32_e32 v19, 1.0, v19
	v_mul_f32_e32 v20, 0xbfb8aa3b, v20
	v_rcp_f32_e32 v19, v19
	s_waitcnt vmcnt(4)
	v_mfma_f32_32x32x16_bf16 v[2:17], v[50:53], v[78:81], v[2:17]
	v_exp_f32_e32 v20, v20
	v_mul_f32_e32 v0, v0, v28
	v_mul_f32_e32 v18, v18, v29
	ds_write2st64_b32 v68, v0, v18 offset0:42 offset1:43
	v_mul_f32_e32 v0, v19, v30
	v_add_f32_e32 v18, 1.0, v20
	v_lshlrev_b32_e32 v19, 16, v123
	s_waitcnt vmcnt(3)
	v_mfma_f32_32x32x16_bf16 v[2:17], v[46:49], v[82:85], v[2:17]
	v_lshlrev_b32_e32 v20, 16, v124
	v_mul_f32_e32 v19, 0xbfb8aa3b, v19
	v_mul_f32_e32 v20, 0xbfb8aa3b, v20
	v_exp_f32_e32 v19, v19
	v_exp_f32_e32 v20, v20
	v_rcp_f32_e32 v18, v18
	v_add_f32_e32 v19, 1.0, v19
	s_waitcnt vmcnt(2)
; __device__ __forceinline__ float sigm_(float x) { return __builtin_amdgcn_rcpf(1.0f + __builtin_amdgcn_exp2f(-1.4426950408889634f * x)); }
; __device__ __forceinline__ void attn_unit_pp(int b, int h, int qb, int par, const bf16_t* __restrict__ QBp, const bf16_t* __restrict__ KBp, const bf16_t* __restrict__ VBp, ...
;     ...
;     for (int dp = 0; dp < 2; ++dp) {
;       bf16x8 wp[2][8];
; #pragma unroll
;       for (int e = 0; e < 2; ++e)
; #pragma unroll
;         for (int ks = 0; ks < 8; ++ks) wp[e][ks] = ld8(wpb + (dp * 2 + e) * 32 * 128 + ks * 16);
; #pragma unroll
;       for (int e = 0; e < 2; ++e) { const int d0 = dp * 2 + e; f32x16 acc = f32x16{};
; #pragma unroll
;         for (int ks = 0; ks < 8; ++ks) acc = __builtin_amdgcn_mfma_f32_32x32x16_bf16(pf[ks], wp[e][ks], acc, 0, 0, 0);
; #pragma unroll
;         for (int r = 0; r < 16; ++r) pgs[(d0 * 16 + r) * 64] = sigm_(__uint_as_float(gate16[r * 4 + d0] << 16)) * acc[r]; }
;     }
;     __syncthreads();
	v_mfma_f32_32x32x16_bf16 v[2:17], v[42:45], v[94:97], v[2:17]
	v_add_f32_e32 v20, 1.0, v20
	v_rcp_f32_e32 v19, v19
	v_rcp_f32_e32 v20, v20
	v_mul_f32_e32 v18, v18, v31
	ds_write2st64_b32 v68, v0, v18 offset0:44 offset1:45
	v_mul_f32_e32 v0, v19, v32
	v_mul_f32_e32 v18, v20, v33
	s_waitcnt vmcnt(1)
	v_mfma_f32_32x32x16_bf16 v[2:17], v[38:41], v[86:89], v[2:17]
	ds_write2st64_b32 v68, v0, v18 offset0:46 offset1:47
	v_lshlrev_b32_e32 v0, 16, v102
	v_lshlrev_b32_e32 v18, 16, v101
	v_mul_f32_e32 v0, 0xbfb8aa3b, v0
	v_mul_f32_e32 v18, 0xbfb8aa3b, v18
	v_exp_f32_e32 v0, v0
	v_exp_f32_e32 v18, v18
	s_waitcnt vmcnt(0)
	v_mfma_f32_32x32x16_bf16 v[2:17], v[34:37], v[134:137], v[2:17]
	v_lshlrev_b32_e32 v19, 16, v104
	v_add_f32_e32 v0, 1.0, v0
	v_add_f32_e32 v18, 1.0, v18
	v_rcp_f32_e32 v0, v0
	v_rcp_f32_e32 v18, v18
	v_mul_f32_e32 v19, 0xbfb8aa3b, v19
	v_exp_f32_e32 v19, v19
	s_nop 4
	v_mul_f32_e32 v0, v0, v2
	v_mul_f32_e32 v2, v18, v3
	ds_write2st64_b32 v68, v0, v2 offset0:48 offset1:49
	v_lshlrev_b32_e32 v2, 16, v103
	v_add_f32_e32 v0, 1.0, v19
	v_mul_f32_e32 v2, 0xbfb8aa3b, v2
	v_lshlrev_b32_e32 v3, 16, v106
	v_rcp_f32_e32 v0, v0
	v_exp_f32_e32 v2, v2
	v_mul_f32_e32 v3, 0xbfb8aa3b, v3
	v_exp_f32_e32 v3, v3
	v_mul_f32_e32 v0, v0, v4
	v_add_f32_e32 v2, 1.0, v2
	v_lshlrev_b32_e32 v4, 16, v105
	v_rcp_f32_e32 v2, v2
	v_add_f32_e32 v3, 1.0, v3
	v_mul_f32_e32 v4, 0xbfb8aa3b, v4
	v_rcp_f32_e32 v3, v3
	v_exp_f32_e32 v4, v4
	v_mul_f32_e32 v2, v2, v5
	ds_write2st64_b32 v68, v0, v2 offset0:50 offset1:51
	v_mul_f32_e32 v0, v3, v6
	v_add_f32_e32 v2, 1.0, v4
	v_lshlrev_b32_e32 v3, 16, v108
	v_lshlrev_b32_e32 v4, 16, v107
	v_mul_f32_e32 v3, 0xbfb8aa3b, v3
	v_mul_f32_e32 v4, 0xbfb8aa3b, v4
	v_exp_f32_e32 v3, v3
	v_exp_f32_e32 v4, v4
	v_rcp_f32_e32 v2, v2
	v_add_f32_e32 v3, 1.0, v3
	v_add_f32_e32 v4, 1.0, v4
	v_rcp_f32_e32 v3, v3
	v_rcp_f32_e32 v4, v4
	v_mul_f32_e32 v2, v2, v7
	ds_write2st64_b32 v68, v0, v2 offset0:52 offset1:53
	v_mul_f32_e32 v0, v3, v8
	v_mul_f32_e32 v2, v4, v9
	v_lshlrev_b32_e32 v3, 16, v110
	v_lshlrev_b32_e32 v4, 16, v109
	v_mul_f32_e32 v3, 0xbfb8aa3b, v3
	v_mul_f32_e32 v4, 0xbfb8aa3b, v4
	v_exp_f32_e32 v3, v3
	v_exp_f32_e32 v4, v4
	ds_write2st64_b32 v68, v0, v2 offset0:54 offset1:55
	v_add_f32_e32 v0, 1.0, v3
	v_add_f32_e32 v2, 1.0, v4
	v_rcp_f32_e32 v0, v0
	v_rcp_f32_e32 v2, v2
	v_lshlrev_b32_e32 v3, 16, v112
	v_mul_f32_e32 v3, 0xbfb8aa3b, v3
	v_exp_f32_e32 v3, v3
	v_mul_f32_e32 v0, v0, v10
	v_mul_f32_e32 v2, v2, v11
	ds_write2st64_b32 v68, v0, v2 offset0:56 offset1:57
	v_lshlrev_b32_e32 v2, 16, v111
	v_add_f32_e32 v0, 1.0, v3
	v_mul_f32_e32 v2, 0xbfb8aa3b, v2
	v_lshlrev_b32_e32 v3, 16, v114
	v_exp_f32_e32 v2, v2
	v_mul_f32_e32 v3, 0xbfb8aa3b, v3
	v_exp_f32_e32 v3, v3
	v_lshlrev_b32_e32 v4, 16, v113
	v_add_f32_e32 v2, 1.0, v2
	v_rcp_f32_e32 v0, v0
	v_rcp_f32_e32 v2, v2
	v_add_f32_e32 v3, 1.0, v3
	v_mul_f32_e32 v4, 0xbfb8aa3b, v4
	v_rcp_f32_e32 v3, v3
	v_exp_f32_e32 v4, v4
	v_mul_f32_e32 v0, v0, v12
	v_mul_f32_e32 v2, v2, v13
	ds_write2st64_b32 v68, v0, v2 offset0:58 offset1:59
	v_mul_f32_e32 v0, v3, v14
	v_add_f32_e32 v2, 1.0, v4
	v_lshlrev_b32_e32 v3, 16, v116
	v_lshlrev_b32_e32 v4, 16, v115
	v_mul_f32_e32 v3, 0xbfb8aa3b, v3
	v_mul_f32_e32 v4, 0xbfb8aa3b, v4
	v_exp_f32_e32 v3, v3
	v_exp_f32_e32 v4, v4
	v_rcp_f32_e32 v2, v2
	v_add_f32_e32 v3, 1.0, v3
	v_add_f32_e32 v4, 1.0, v4
	v_rcp_f32_e32 v3, v3
	v_rcp_f32_e32 v4, v4
	v_mul_f32_e32 v2, v2, v15
	ds_write2st64_b32 v68, v0, v2 offset0:60 offset1:61
	v_mul_f32_e32 v0, v3, v16
	v_mul_f32_e32 v2, v4, v17
	ds_write2st64_b32 v68, v0, v2 offset0:62 offset1:63
	s_waitcnt lgkmcnt(0)
	s_barrier
	s_branch .LBB0_338
